# nt cache policy on the short-conv main-row loads (cg/xin/bg, 12 loads per item), otherwise the P2b-ring version
# speedup vs baseline: 1.0034x; 1.0034x over previous
.Lcv_hd:
	global_load_dwordx4 v[40:43], v155, s[6:7] offset:2048 nt
	global_load_dwordx4 v[44:47], v156, s[6:7] nt
	global_load_dwordx4 v[48:51], v155, s[6:7] nt
	s_add_u32 s6, s6, 0x4800
	s_addc_u32 s7, s7, 0
	global_load_dwordx4 v[52:55], v155, s[6:7] offset:2048 nt
	global_load_dwordx4 v[56:59], v156, s[6:7] nt
	global_load_dwordx4 v[60:63], v155, s[6:7] nt
	s_add_u32 s6, s6, 0x4800
	s_addc_u32 s7, s7, 0
	global_load_dwordx4 v[64:67], v155, s[6:7] offset:2048 nt
	global_load_dwordx4 v[68:71], v156, s[6:7] nt
	global_load_dwordx4 v[72:75], v155, s[6:7] nt
	s_add_u32 s6, s6, 0x4800
	s_addc_u32 s7, s7, 0
	global_load_dwordx4 v[76:79], v155, s[6:7] offset:2048 nt
	global_load_dwordx4 v[80:83], v156, s[6:7] nt
	global_load_dwordx4 v[84:87], v155, s[6:7] nt
	s_lshl_b32 s5, s52, 12
	s_add_u32 s40, s34, s5
	s_addc_u32 s41, s35, 0
	s_add_u32 s40, s40, 0x17200800
	s_addc_u32 s41, s41, 0
	s_waitcnt vmcnt(0)
	s_cmp_eq_u32 s101, 1
	s_cbranch_scc0 .Lcv_nh
	v_lshlrev_b32_e32 v88, 16, v24
	v_lshlrev_b32_e32 v89, 16, v28
	v_mul_f32_e32 v100, v88, v89
	v_and_b32_e32 v90, 0xffff0000, v24
	v_and_b32_e32 v91, 0xffff0000, v28
	v_mul_f32_e32 v101, v90, v91
	v_lshlrev_b32_e32 v88, 16, v25
	v_lshlrev_b32_e32 v89, 16, v29
	v_mul_f32_e32 v102, v88, v89
	v_and_b32_e32 v90, 0xffff0000, v25
	v_and_b32_e32 v91, 0xffff0000, v29
	v_mul_f32_e32 v103, v90, v91
	v_lshlrev_b32_e32 v88, 16, v26
	v_lshlrev_b32_e32 v89, 16, v30
	v_mul_f32_e32 v104, v88, v89
	v_and_b32_e32 v90, 0xffff0000, v26
	v_and_b32_e32 v91, 0xffff0000, v30
	v_mul_f32_e32 v105, v90, v91
	v_lshlrev_b32_e32 v88, 16, v27
	v_lshlrev_b32_e32 v89, 16, v31
	v_mul_f32_e32 v106, v88, v89
	v_and_b32_e32 v90, 0xffff0000, v27
	v_and_b32_e32 v91, 0xffff0000, v31
	v_mul_f32_e32 v107, v90, v91
	v_lshlrev_b32_e32 v88, 16, v32
	v_lshlrev_b32_e32 v89, 16, v36
	v_mul_f32_e32 v108, v88, v89
	v_and_b32_e32 v90, 0xffff0000, v32
	v_and_b32_e32 v91, 0xffff0000, v36
	v_mul_f32_e32 v109, v90, v91
	v_lshlrev_b32_e32 v88, 16, v33
	v_lshlrev_b32_e32 v89, 16, v37
	v_mul_f32_e32 v110, v88, v89
	v_and_b32_e32 v90, 0xffff0000, v33
	v_and_b32_e32 v91, 0xffff0000, v37
	v_mul_f32_e32 v111, v90, v91
	v_lshlrev_b32_e32 v88, 16, v34
	v_lshlrev_b32_e32 v89, 16, v38
	v_mul_f32_e32 v112, v88, v89
	v_and_b32_e32 v90, 0xffff0000, v34
	v_and_b32_e32 v91, 0xffff0000, v38
	v_mul_f32_e32 v113, v90, v91
	v_lshlrev_b32_e32 v88, 16, v35
	v_lshlrev_b32_e32 v89, 16, v39
	v_mul_f32_e32 v114, v88, v89
	v_and_b32_e32 v90, 0xffff0000, v35
	v_and_b32_e32 v91, 0xffff0000, v39
	v_mul_f32_e32 v115, v90, v91
